# P6: K tile global loads issued first and K written to its free LDS buffer before barrier 1; only V writes remain between the two barriers
# speedup vs baseline: 1.0246x; 1.0048x over previous
; template <int VB, bool SK>
; __device__ __forceinline__ void pv_tile(f32x16* o, int vb0, bf16x8 pa0, bf16x8 pa1, bf16x8 pa2, bf16x8 pa3, bool act) {
;     if (SK && !act) return;
;     ...
;     PV_D0(0); PV_D0(1); PV_D0(2); PV_D0(3);
.LBB0_1336:
	s_mov_b32 s20, 0x1000000
	v_add_co_u32_e32 v2, vcc, s20, v214
	s_nop 1
	v_addc_co_u32_e32 v3, vcc, 0, v215, vcc
	s_waitcnt vmcnt(2)
	v_add_co_u32_e32 v6, vcc, 0x1002000, v214
	s_nop 1
	v_addc_co_u32_e32 v7, vcc, 0, v215, vcc
	v_add_co_u32_e32 v14, vcc, 0x2000, v214
	s_nop 1
	v_addc_co_u32_e32 v15, vcc, 0, v215, vcc
	global_load_dwordx4 v[10:13], v[214:215], off
	global_load_dwordx4 v[208:211], v[14:15], off
	global_load_dwordx4 v[2:5], v[2:3], off
	s_nop 0
	global_load_dwordx4 v[6:9], v[6:7], off
	s_and_b64 vcc, exec, s[6:7]
	s_cbranch_vccnz .LBB0_1338
	s_waitcnt vmcnt(7)
	ds_read_b64_tr_b16 v[144:145], v226 offset:0
	ds_read_b64_tr_b16 v[146:147], v226 offset:0x800
	s_waitcnt vmcnt(6)
	ds_read_b64_tr_b16 v[148:149], v226 offset:0x1000
	ds_read_b64_tr_b16 v[150:151], v226 offset:0x1800
	s_waitcnt vmcnt(5)
	ds_read_b64_tr_b16 v[152:153], v226 offset:0x2000
	ds_read_b64_tr_b16 v[154:155], v226 offset:0x2800
	s_waitcnt vmcnt(4)
	ds_read_b64_tr_b16 v[156:157], v226 offset:0x3000
	ds_read_b64_tr_b16 v[158:159], v226 offset:0x3800
	s_waitcnt lgkmcnt(0)
	v_mfma_f32_32x32x16_bf16 v[64:79], v[192:195], v[144:147], v[64:79]
	ds_read_b64_tr_b16 v[144:145], v226 offset:0x200
	ds_read_b64_tr_b16 v[146:147], v226 offset:0xa00
	v_mfma_f32_32x32x16_bf16 v[64:79], v[196:199], v[148:151], v[64:79]
	ds_read_b64_tr_b16 v[148:149], v226 offset:0x1200
	ds_read_b64_tr_b16 v[150:151], v226 offset:0x1a00
	v_mfma_f32_32x32x16_bf16 v[64:79], v[200:203], v[152:155], v[64:79]
	ds_read_b64_tr_b16 v[152:153], v226 offset:0x2200
	ds_read_b64_tr_b16 v[154:155], v226 offset:0x2a00
	v_mfma_f32_32x32x16_bf16 v[64:79], v[204:207], v[156:159], v[64:79]
	ds_read_b64_tr_b16 v[156:157], v226 offset:0x3200
	ds_read_b64_tr_b16 v[158:159], v226 offset:0x3a00
	s_waitcnt lgkmcnt(0)
	v_mfma_f32_32x32x16_bf16 v[48:63], v[192:195], v[144:147], v[48:63]
	ds_read_b64_tr_b16 v[144:145], v226 offset:0x400
	ds_read_b64_tr_b16 v[146:147], v226 offset:0xc00
	v_mfma_f32_32x32x16_bf16 v[48:63], v[196:199], v[148:151], v[48:63]
	ds_read_b64_tr_b16 v[148:149], v226 offset:0x1400
	ds_read_b64_tr_b16 v[150:151], v226 offset:0x1c00
	v_mfma_f32_32x32x16_bf16 v[48:63], v[200:203], v[152:155], v[48:63]
	ds_read_b64_tr_b16 v[152:153], v226 offset:0x2400
	ds_read_b64_tr_b16 v[154:155], v226 offset:0x2c00
	v_mfma_f32_32x32x16_bf16 v[48:63], v[204:207], v[156:159], v[48:63]
	ds_read_b64_tr_b16 v[156:157], v226 offset:0x3400
	ds_read_b64_tr_b16 v[158:159], v226 offset:0x3c00
	s_waitcnt lgkmcnt(0)
	v_mfma_f32_32x32x16_bf16 v[32:47], v[192:195], v[144:147], v[32:47]
	ds_read_b64_tr_b16 v[144:145], v226 offset:0x600
	ds_read_b64_tr_b16 v[146:147], v226 offset:0xe00
	v_mfma_f32_32x32x16_bf16 v[32:47], v[196:199], v[148:151], v[32:47]
	ds_read_b64_tr_b16 v[148:149], v226 offset:0x1600
	ds_read_b64_tr_b16 v[150:151], v226 offset:0x1e00
	v_mfma_f32_32x32x16_bf16 v[32:47], v[200:203], v[152:155], v[32:47]
	ds_read_b64_tr_b16 v[152:153], v226 offset:0x2600
	ds_read_b64_tr_b16 v[154:155], v226 offset:0x2e00
	v_mfma_f32_32x32x16_bf16 v[32:47], v[204:207], v[156:159], v[32:47]
	ds_read_b64_tr_b16 v[156:157], v226 offset:0x3600
	ds_read_b64_tr_b16 v[158:159], v226 offset:0x3e00
	s_waitcnt lgkmcnt(0)
	v_mfma_f32_32x32x16_bf16 v[16:31], v[192:195], v[144:147], v[16:31]
	v_mfma_f32_32x32x16_bf16 v[16:31], v[196:199], v[148:151], v[16:31]
	v_mfma_f32_32x32x16_bf16 v[16:31], v[200:203], v[152:155], v[16:31]
	v_mfma_f32_32x32x16_bf16 v[16:31], v[204:207], v[156:159], v[16:31]

.LBB0_1374:
	s_waitcnt vmcnt(2)
	ds_write_b128 v223, v[10:13] offset:32768
	ds_write_b128 v223, v[208:211] offset:40960
	s_barrier
	s_waitcnt vmcnt(0)
	v_cmp_gt_f32_e32 vcc, 1.0, v14
	ds_write_b128 v235, v[2:5]
	ds_write_b128 v235, v[6:9] offset:8192
	s_cbranch_vccz .LBB0_1378
	s_and_saveexec_b64 s[6:7], s[2:3]
	ds_write_b32 v225, v14 offset:128
	s_or_b64 exec, exec, s[6:7]
	s_waitcnt lgkmcnt(0)
	ds_read_b128 v[144:147], v224 offset:224
	ds_read_b128 v[148:151], v224 offset:192
	ds_read_b128 v[152:155], v224 offset:160
	ds_read_b128 v[156:159], v224 offset:128
	s_waitcnt lgkmcnt(3)
	v_pk_mul_f32 v[78:79], v[78:79], v[146:147]
	s_waitcnt lgkmcnt(2)
	v_pk_mul_f32 v[74:75], v[74:75], v[150:151]
	s_waitcnt lgkmcnt(1)
	v_pk_mul_f32 v[70:71], v[70:71], v[154:155]
	s_waitcnt lgkmcnt(0)
	v_pk_mul_f32 v[66:67], v[66:67], v[158:159]
	v_pk_mul_f32 v[76:77], v[76:77], v[144:145]
	v_pk_mul_f32 v[72:73], v[72:73], v[148:149]
	v_pk_mul_f32 v[68:69], v[68:69], v[152:153]
	v_pk_mul_f32 v[64:65], v[64:65], v[156:157]
	v_pk_mul_f32 v[62:63], v[62:63], v[146:147]
	v_pk_mul_f32 v[58:59], v[58:59], v[150:151]
	v_pk_mul_f32 v[54:55], v[54:55], v[154:155]
	v_pk_mul_f32 v[50:51], v[50:51], v[158:159]
	v_pk_mul_f32 v[60:61], v[60:61], v[144:145]
	v_pk_mul_f32 v[56:57], v[56:57], v[148:149]
	v_pk_mul_f32 v[52:53], v[52:53], v[152:153]
	v_pk_mul_f32 v[48:49], v[48:49], v[156:157]
	v_pk_mul_f32 v[46:47], v[46:47], v[146:147]
	v_pk_mul_f32 v[42:43], v[42:43], v[150:151]
	v_pk_mul_f32 v[38:39], v[38:39], v[154:155]
	v_pk_mul_f32 v[34:35], v[34:35], v[158:159]
	v_pk_mul_f32 v[44:45], v[44:45], v[144:145]
	v_pk_mul_f32 v[40:41], v[40:41], v[148:149]
	v_pk_mul_f32 v[36:37], v[36:37], v[152:153]
	v_pk_mul_f32 v[32:33], v[32:33], v[156:157]
	v_pk_mul_f32 v[30:31], v[30:31], v[146:147]
	v_pk_mul_f32 v[26:27], v[26:27], v[150:151]
	v_pk_mul_f32 v[22:23], v[22:23], v[154:155]
	v_pk_mul_f32 v[18:19], v[18:19], v[158:159]
	v_pk_mul_f32 v[28:29], v[28:29], v[144:145]
	v_pk_mul_f32 v[24:25], v[24:25], v[148:149]
	v_pk_mul_f32 v[20:21], v[20:21], v[152:153]
	v_pk_mul_f32 v[16:17], v[16:17], v[156:157]

.LBB0_1389:
	v_add_co_u32_e32 v2, vcc, 0x1004000, v214
	s_nop 1
	v_addc_co_u32_e32 v3, vcc, 0, v215, vcc
	v_add_co_u32_e32 v6, vcc, 0x1006000, v214
	s_nop 1
	v_addc_co_u32_e32 v7, vcc, 0, v215, vcc
	v_add_co_u32_e32 v10, vcc, 0x4000, v214
	s_nop 1
	v_addc_co_u32_e32 v11, vcc, 0, v215, vcc
	v_add_co_u32_e32 v14, vcc, 0x6000, v214
	s_nop 1
	v_addc_co_u32_e32 v15, vcc, 0, v215, vcc
	global_load_dwordx4 v[10:13], v[10:11], off
	s_nop 0
	global_load_dwordx4 v[208:211], v[14:15], off
	global_load_dwordx4 v[2:5], v[2:3], off
	s_nop 0
	global_load_dwordx4 v[6:9], v[6:7], off
	s_and_b64 vcc, exec, s[4:5]
	s_cbranch_vccnz .LBB0_1388

.LBB0_1426:
	s_andn2_b64 vcc, exec, s[86:87]
	s_cbranch_vccnz .Lselb_nokw
	s_waitcnt vmcnt(2)
	ds_write_b128 v223, v[10:13] offset:49152
	ds_write_b128 v223, v[208:211] offset:57344
.Lselb_nokw:
	s_barrier
	s_cbranch_vccnz .LBB0_1428
	s_waitcnt vmcnt(0)
	ds_write_b128 v235, v[2:5] offset:16384
	ds_write_b128 v235, v[6:9] offset:24576
